# NSA attention units: branch gates and compressed-branch rows loaded at unit set-up instead of blocking loads between and after the passes
# speedup vs baseline: 1.0116x; 1.0031x over previous
; template <int DQK, int MODE> ...
;     ...
;     const int tid = make_tid(wave0), lane = tid & 63, r32 = lane & 31, hi = lane >> 5;
;     const int wid = wave0;
;     const int tw0 = t0 + 32 * wid, tq = tw0 + r32;
;     bf16x8 qf[NDS];
; #pragma unroll
;     for (int ds = 0; ds < NDS; ++ds) qf[ds] = *(const bf16x8*)(Qp + (size_t)tq * qs + 16 * ds + 8 * hi);
;     int kt_lo = 0; const int kt_hi = (t0 >> 6) + 3;
;     if (MODE == 1) { const int lo = t0 - 511; kt_lo = lo > 0 ? (lo >> 6) : 0; }
;     unsigned long long selm = 0ull; if (MODE == 2) selm = selp[tq];
;     const int kc0 = wid % CPR, kc1 = (8 + (wid & 3)) % CPR;
;     const bf16_t* ksrc0 = Kp + (size_t)lane * ks + kc0 * 8;
;     const bf16_t* ksrc1 = Kp + (size_t)lane * ks + kc1 * 8;
;     const bf16_t* vsrc = Vp + (size_t)(16 * (wid & 3) + (lane >> 2)) * vs + (wid >> 2) * 32 + (lane & 3) * 8;
;     ...
;     o[0] = f32x16{}; o[1] = f32x16{};
;     float m_run = 0.f, l_run = 0.f; bool init = false;
;     f32x16 negm = f32x16{}; asm volatile("" : "+v"(negm));
;     f32x16 pa0 = f32x16{}, pa1 = f32x16{}, pb0 = f32x16{}, pb1 = f32x16{};
;     bf16x8 kf[2 * NDS];
;     AT_DMAK(kt_lo); AT_DMAV(kt_lo); AT_DMAK(kt_lo + 1); AT_DMAK(kt_lo + 2); AT_DMAV(kt_lo + 1);
; __device__ __forceinline__ void attn_phase(LAS unsigned char* lds, int* counter, const bf16_t* __restrict__ P, const bf16_t* __restrict__ Qm, const bf16_t* __restrict__ Kmla, ...
;     ...
;             const int b = (r - 64) >> 3, head = (r - 64) & 7, g = head >> 2;
;             const bf16_t* Pb = P + (size_t)b * SEQ * NPJ;
;             attn_pass<64, 2>(lds, Pb + C_NQ + head * 64, NPJ, Pb + C_NKV + 256 + g * 64, NPJ, Pb + C_NKV + 384 + g * 64, NPJ, t0, mask + (size_t)(b * 2 + g) * SEQ, o, linv, wave0);
;             const size_t row = (size_t)b * SEQ + tq;
;             osave(lds, tid, o, linv * gates[row * 24 + head * 3 + 1]);
;             attn_pass<64, 1>(lds, Pb + C_NQ + head * 64, NPJ, Pb + C_NKV + 512 + g * 64, NPJ, Pb + C_NKV + 640 + g * 64, NPJ, t0, nullptr, o, linv, wave0);
;             const float g0 = gates[row * 24 + head * 3 + 0], sc2 = linv * gates[row * 24 + head * 3 + 2];
;             const bf16_t* oc = ocmp + row * 512 + head * 64;
; #pragma unroll
;             for (int dh = 0; dh < 2; ++dh)
; #pragma unroll
;                 for (int a = 0; a < 4; ++a) {
;                     const u32x2 raw = *(const u32x2*)(oc + 32 * dh + 8 * a + 4 * hi);
.LBB0_683:
	s_not_b32 s2, s5
	s_lshl_b32 s2, s2, 8
	s_and_b32 s40, s2, 0xf00
	s_add_i32 s39, s40, s55
	v_bfe_u32 v190, v191, 5, 1
	v_and_or_b32 v214, v191, 31, s39
	s_cmp_gt_i32 s41, 31
	s_mov_b64 s[2:3], -1
	s_cbranch_scc0 .LBB0_728
	s_cmp_gt_u32 s41, 63
	s_cbranch_scc0 .LBB0_713
	s_sub_i32 s2, s41, 64
	s_lshr_b32 s22, s2, 3
	s_and_b32 s47, s41, 7
	s_bfe_u32 s4, s41, 0x10002
	s_mul_i32 s3, s22, 0x1400000
	v_readlane_b32 s6, v254, 48
	s_mul_hi_u32 s2, s22, 0x1400000
	v_readlane_b32 s7, v254, 49
	s_add_u32 s45, s6, s3
	s_addc_u32 s44, s7, s2
	s_lshl_b32 s42, s47, 6
	s_lshl_b32 s2, s47, 7
	s_add_u32 s16, s45, s2
	s_addc_u32 s17, s44, 0
	s_lshl_b32 s46, s4, 6
	s_lshl_b32 s2, s4, 7
	s_add_u32 s2, s45, s2
	s_addc_u32 s3, s44, 0
	v_lshl_add_u32 v222, s22, 12, v214
	v_mov_b32_e32 v223, v215
	v_mov_b64_e32 v[224:225], s[10:11]
	v_mad_u64_u32 v[224:225], s[6:7], v222, s85, v[224:225]
	s_mul_i32 s80, s47, 12
	v_lshl_add_u64 v[224:225], v[224:225], 0, s[80:81]
	global_load_dword v204, v[224:225], off
	global_load_dword v205, v[224:225], off offset:4
	global_load_dword v206, v[224:225], off offset:8
	v_lshlrev_b64 v[226:227], 10, v[222:223]
	v_lshl_add_u64 v[226:227], s[8:9], 0, v[226:227]
	s_lshl_b32 s80, s42, 1
	v_lshl_add_u64 v[226:227], v[226:227], 0, s[80:81]
	v_lshlrev_b32_e32 v228, 3, v190
	v_mov_b32_e32 v229, v215
	v_lshl_add_u64 v[226:227], v[226:227], 0, v[228:229]
	global_load_dwordx2 v[208:209], v[226:227], off
	global_load_dwordx2 v[210:211], v[226:227], off offset:16
	global_load_dwordx2 v[212:213], v[226:227], off offset:32
	global_load_dwordx2 v[216:217], v[226:227], off offset:48
	global_load_dwordx2 v[218:219], v[226:227], off offset:64
	global_load_dwordx2 v[220:221], v[226:227], off offset:80
	global_load_dwordx2 v[230:231], v[226:227], off offset:96
	global_load_dwordx2 v[232:233], v[226:227], off offset:112
	s_lshl_b32 s5, s22, 1
	s_or_b32 s80, s5, s4
	s_lshl_b64 s[4:5], s[80:81], 15
	v_mov_b32_e32 v20, v246
	s_add_u32 s4, s34, s4
	s_addc_u32 s5, s35, s5
	v_and_b32_e32 v21, 31, v20
	v_or_b32_e32 v0, s39, v21
	v_mov_b32_e32 v1, v215
	v_lshl_add_u64 v[2:3], v[0:1], 3, s[4:5]
	global_load_dwordx2 v[144:145], v[2:3], off
	v_bfe_u32 v22, v20, 5, 1
	v_mov_b64_e32 v[2:3], s[16:17]
	v_mad_u64_u32 v[0:1], s[4:5], v0, s65, v[2:3]
	v_lshlrev_b32_e32 v2, 4, v22
	v_mov_b32_e32 v3, v215
	v_lshl_add_u64 v[0:1], v[0:1], 0, v[2:3]
	global_load_dwordx4 v[96:99], v[0:1], off offset:2368
	global_load_dwordx4 v[100:103], v[0:1], off offset:2400
	global_load_dwordx4 v[104:107], v[0:1], off offset:2432
	global_load_dwordx4 v[108:111], v[0:1], off offset:2464
	v_and_b32_e32 v4, 63, v20
	v_mul_u32_u24_e32 v0, 0xa00, v4
	v_lshlrev_b32_e32 v0, 1, v0
	v_mov_b32_e32 v1, v215
	v_lshl_add_u64 v[0:1], s[2:3], 0, v[0:1]
	s_lshl_b32 s18, s58, 1
	s_mov_b32 s19, s81
	v_lshl_add_u64 v[146:147], v[0:1], 0, s[18:19]
	v_bfe_u32 v0, v20, 2, 4
	v_or_b32_e32 v0, s59, v0
	v_mul_u32_u24_e32 v0, 0xa00, v0
	v_lshlrev_b32_e32 v0, 1, v0
	v_mov_b32_e32 v1, v215
	v_lshlrev_b32_e32 v2, 3, v20
	v_lshl_add_u64 v[0:1], s[2:3], 0, v[0:1]
	s_lshl_b32 s20, s60, 1
	s_mov_b32 s21, s81
	v_and_b32_e32 v23, 24, v2
	s_mov_b64 s[4:5], 0xf40
	v_lshl_add_u64 v[0:1], v[0:1], 0, s[20:21]
	v_lshlrev_b32_e32 v2, 1, v23
	s_mov_b32 m0, s61
	v_lshl_add_u64 v[16:17], v[146:147], 0, s[4:5]
	v_lshl_add_u64 v[18:19], v[0:1], 0, v[2:3]
	s_mov_b64 s[2:3], 0x1040
	v_mov_b32_e32 v0, v215
	v_mov_b32_e32 v1, v215
	v_mov_b32_e32 v2, v215
	v_mov_b32_e32 v4, v215
	v_mov_b32_e32 v5, v215
	v_mov_b32_e32 v6, v215
	v_mov_b32_e32 v7, v215
	v_mov_b32_e32 v8, v215
	v_mov_b32_e32 v9, v215
	v_mov_b32_e32 v10, v215
	v_mov_b32_e32 v11, v215
	v_mov_b32_e32 v12, v215
	v_mov_b32_e32 v13, v215
	v_mov_b32_e32 v14, v215
	v_mov_b32_e32 v15, v215
	v_lshl_add_u64 v[148:149], v[18:19], 0, s[2:3]
	global_load_lds_dwordx4 v[16:17], off
	s_mov_b32 m0, s82
	s_mov_b64 s[2:3], 0x50f40
	global_load_lds_dwordx4 v[148:149], off
	v_lshl_add_u64 v[0:1], v[146:147], 0, s[2:3]
	s_mov_b32 m0, s69
	s_mov_b64 s[2:3], 0xa0f40
	global_load_lds_dwordx4 v[0:1], off
	v_lshl_add_u64 v[0:1], v[146:147], 0, s[2:3]
	s_mov_b32 m0, s68
	s_mov_b64 s[2:3], 0x51040
	global_load_lds_dwordx4 v[0:1], off
	v_lshl_add_u64 v[0:1], v[18:19], 0, s[2:3]
	s_mov_b32 m0, s83
	v_lshlrev_b32_e32 v151, 10, v22
	global_load_lds_dwordx4 v[0:1], off
	v_lshlrev_b32_e32 v152, 4, v21
	s_waitcnt vmcnt(2) lgkmcnt(0)
	s_barrier
; #define AT_DMAV(t) do { const int t_ = AT_CL(t); LAS unsigned char* d_ = lds + (t_ % 3) * SLOT + KSL; \
;         __builtin_amdgcn_global_load_lds((const GAS unsigned*)(vsrc + (size_t)t_ * 64 * vs), (LAS unsigned*)(d_ + wid * 1024), 16, 0, 0); } while (0)
; #define AT_WAITBAR(N) asm volatile("s_waitcnt vmcnt(" #N ") lgkmcnt(0)\n\ts_barrier" ::: "memory")
; #define AT_KFRAG(t) do { \
;         LAS unsigned char* Kb_ = lds + ((t) % 3) * SLOT + hi * 1024 + r32 * 16; \
;         _Pragma("unroll") for (int ds = 0; ds < NDS; ++ds) { kf[2 * ds] = *(LAS bf16x8*)(Kb_ + ds * 2048); kf[2 * ds + 1] = *(LAS bf16x8*)(Kb_ + ds * 2048 + 512); } } while (0)
; template <int DQK, int MODE> ...
;     ...
;     o[0] = f32x16{}; o[1] = f32x16{};
;     float m_run = 0.f, l_run = 0.f; bool init = false;
;     f32x16 negm = f32x16{}; asm volatile("" : "+v"(negm));
;     f32x16 pa0 = f32x16{}, pa1 = f32x16{}, pb0 = f32x16{}, pb1 = f32x16{};
;     bf16x8 kf[2 * NDS];
;     AT_DMAK(kt_lo); AT_DMAV(kt_lo); AT_DMAK(kt_lo + 1); AT_DMAK(kt_lo + 2); AT_DMAV(kt_lo + 1);
;     if (NKW > 1) AT_WAITBAR(3); else AT_WAITBAR(2);
;     { AT_KFRAG(kt_lo); asm volatile("s_waitcnt lgkmcnt(0)\n\ts_barrier" ::: "memory");
;       const float b_ = AT_BIAS(kt_lo); AT_QKM(pa0, pa1, AT_SPLAT(b_)); }
;     const int vfo = ((lane >> 4) & 1) * 32 + (lane & 3) * 8 + (4 * hi + ((lane & 15) >> 2)) * 64;
	v_add3_u32 v153, 0, v151, v152
	ds_read_b128 v[0:3], v153
	ds_read_b128 v[4:7], v153 offset:512
	v_mov_b32_e32 v9, v215
	s_lshr_b32 s2, s40, 6
	v_mov_b32_e32 v154, 0
	s_mov_b32 s23, s81
	s_waitcnt vmcnt(2)
	v_and_b32_e32 v8, 1, v144
	v_cmp_eq_u64_e32 vcc, 0, v[8:9]
	s_mov_b32 s19, 1
	s_mov_b32 s21, 4
	v_cndmask_b32_e32 v32, 0, v249, vcc
	v_mov_b32_e32 v33, v32
	v_mov_b32_e32 v34, v32
	v_mov_b32_e32 v35, v32
	v_mov_b32_e32 v36, v32
	v_mov_b32_e32 v37, v32
	v_mov_b32_e32 v38, v32
	v_mov_b32_e32 v39, v32
	v_mov_b32_e32 v40, v32
	v_mov_b32_e32 v41, v32
	v_mov_b32_e32 v42, v32
	v_mov_b32_e32 v43, v32
	v_mov_b32_e32 v44, v32
	v_mov_b32_e32 v45, v32
	v_mov_b32_e32 v46, v32
	v_mov_b32_e32 v47, v32
	s_mov_b32 s48, 0
	s_or_b32 s43, s2, 3
	s_waitcnt lgkmcnt(0)
	v_mfma_f32_32x32x16_bf16 v[48:63], v[0:3], v[96:99], v[32:47]
	s_mov_b64 s[2:3], 0
	s_movk_i32 s49, 0x7f
	v_mov_b32_e32 v150, 0
	v_mov_b32_e32 v8, v154
	v_mov_b32_e32 v9, v154
	v_mov_b32_e32 v10, v154
	v_mov_b32_e32 v11, v154
	v_mfma_f32_32x32x16_bf16 v[32:47], v[4:7], v[96:99], v[32:47]
	ds_read_b128 v[0:3], v153 offset:2048
	ds_read_b128 v[4:7], v153 offset:2560
	v_mov_b32_e32 v12, v154
	v_mov_b32_e32 v13, v154
	v_mov_b32_e32 v14, v154
	v_mov_b32_e32 v15, v154
	v_mov_b32_e32 v16, v154
	v_mov_b32_e32 v17, v154
	s_waitcnt lgkmcnt(1)
	v_mfma_f32_32x32x16_bf16 v[48:63], v[0:3], v[100:103], v[48:63]
	v_mov_b32_e32 v18, v154
	v_mov_b32_e32 v19, v154
	v_mov_b32_e32 v24, v154
	v_mov_b32_e32 v25, v154
	v_mov_b32_e32 v26, v154
	v_mov_b32_e32 v27, v154
	v_mov_b32_e32 v28, v154
	s_waitcnt lgkmcnt(0)
	v_mfma_f32_32x32x16_bf16 v[32:47], v[4:7], v[100:103], v[32:47]
	ds_read_b128 v[0:3], v153 offset:4096
	ds_read_b128 v[4:7], v153 offset:4608
	v_mov_b32_e32 v29, v154
	v_mov_b32_e32 v30, v154
	v_mov_b32_e32 v31, v154
	s_waitcnt lgkmcnt(1)
	v_mfma_f32_32x32x16_bf16 v[48:63], v[0:3], v[104:107], v[48:63]
	s_waitcnt lgkmcnt(0)
	v_mfma_f32_32x32x16_bf16 v[32:47], v[4:7], v[104:107], v[32:47]
	ds_read_b128 v[0:3], v153 offset:6144
	ds_read_b128 v[4:7], v153 offset:6656
	s_waitcnt lgkmcnt(0)
	s_barrier
	s_waitcnt lgkmcnt(1)
	v_mfma_f32_32x32x16_bf16 v[48:63], v[0:3], v[108:111], v[48:63]
	v_lshlrev_b32_e32 v2, 4, v20
	v_lshlrev_b32_e32 v0, 1, v20
	v_and_b32_e32 v2, 0xc0, v2
	v_and_b32_e32 v0, 32, v0
	v_lshl_or_b32 v2, v22, 8, v2
	v_or3_b32 v0, v2, v0, v23
	v_lshlrev_b32_e32 v1, 2, v22
	s_waitcnt lgkmcnt(0)
	v_mfma_f32_32x32x16_bf16 v[32:47], v[4:7], v[108:111], v[32:47]
	v_add_u32_e32 v155, 0, v0
	v_add_u32_e32 v0, s39, v21
	v_sub_u32_e32 v156, v0, v1
	v_mov_b32_e32 v0, 0
	v_mov_b32_e32 v1, v154
	v_mov_b32_e32 v2, v154
	v_mov_b32_e32 v3, v154
	v_mov_b32_e32 v4, v154
	v_mov_b32_e32 v5, v154
	v_mov_b32_e32 v6, v154
	v_mov_b32_e32 v7, v154
	v_mov_b32_e32 v20, v154
	v_mov_b32_e32 v21, v154
	v_mov_b32_e32 v22, v154
	v_mov_b32_e32 v23, v154
	v_readfirstlane_b32 s86, v146
	v_readfirstlane_b32 s87, v147
	v_readfirstlane_b32 s98, v148
	v_readfirstlane_b32 s99, v149
	s_nop 1
	v_subrev_u32_e32 v200, s86, v146
	v_subrev_u32_e32 v202, s98, v148
	s_add_u32 s86, s86, 0xf40
	s_addc_u32 s87, s87, 0
	s_branch .LBB0_689

; __device__ __forceinline__ int make_tid(int wave0) { int t = wave0 * 64 + (int)__builtin_amdgcn_mbcnt_hi(~0u, __builtin_amdgcn_mbcnt_lo(~0u, 0u)); asm volatile("" : "+v"(t)); return t; }
; #define LAS __attribute__((address_space(3)))
; __device__ __forceinline__ float sum32x(float v) { auto rr = __builtin_amdgcn_permlane32_swap(__float_as_uint(v), __float_as_uint(v), false, false); return __uint_as_float(rr[0]) + __uint_as_float(rr[1]); }
; #define AT_DMAV(t) do { const int t_ = AT_CL(t); LAS unsigned char* d_ = lds + (t_ % 3) * SLOT + KSL; \
;         __builtin_amdgcn_global_load_lds((const GAS unsigned*)(vsrc + (size_t)t_ * 64 * vs), (LAS unsigned*)(d_ + wid * 1024), 16, 0, 0); } while (0)
; template <int DQK, int MODE> ...
;     ...
;     const int tid = make_tid(wave0), lane = tid & 63, r32 = lane & 31, hi = lane >> 5;
;     const int wid = wave0;
;     const int tw0 = t0 + 32 * wid, tq = tw0 + r32;
;     bf16x8 qf[NDS];
; #pragma unroll
;     for (int ds = 0; ds < NDS; ++ds) qf[ds] = *(const bf16x8*)(Qp + (size_t)tq * qs + 16 * ds + 8 * hi);
;     int kt_lo = 0; const int kt_hi = (t0 >> 6) + 3;
;     if (MODE == 1) { const int lo = t0 - 511; kt_lo = lo > 0 ? (lo >> 6) : 0; }
;     unsigned long long selm = 0ull; if (MODE == 2) selm = selp[tq];
;     const int kc0 = wid % CPR, kc1 = (8 + (wid & 3)) % CPR;
;     const bf16_t* ksrc0 = Kp + (size_t)lane * ks + kc0 * 8;
;     const bf16_t* ksrc1 = Kp + (size_t)lane * ks + kc1 * 8;
;     const bf16_t* vsrc = Vp + (size_t)(16 * (wid & 3) + (lane >> 2)) * vs + (wid >> 2) * 32 + (lane & 3) * 8;
;     ...
;     o[0] = f32x16{}; o[1] = f32x16{};
;     float m_run = 0.f, l_run = 0.f; bool init = false;
;     f32x16 negm = f32x16{}; asm volatile("" : "+v"(negm));
;     f32x16 pa0 = f32x16{}, pa1 = f32x16{}, pb0 = f32x16{}, pb1 = f32x16{};
;     bf16x8 kf[2 * NDS];
;     AT_DMAK(kt_lo); AT_DMAV(kt_lo); AT_DMAK(kt_lo + 1); AT_DMAK(kt_lo + 2); AT_DMAV(kt_lo + 1);
;     if (NKW > 1) AT_WAITBAR(3); else AT_WAITBAR(2);
;     ...
;     const float lt = sum32x(l_run);
;     linv = lt > 0.f ? 1.0f / lt : 0.f;
; }
; __device__ __forceinline__ void osave(LAS unsigned char* lds, int tid, const f32x16 (&o)[2], float sc) {
;     LAS float* p = (LAS float*)(lds + OSAVE_OFF) + tid;
; #pragma unroll
;     for (int i = 0; i < 16; ++i) { p[i * 512] = o[0][i] * sc; p[(16 + i) * 512] = o[1][i] * sc; }
; }
.LBB0_698:
	v_readlane_b32 s86, v254, 37
	v_readlane_b32 s87, v254, 38
	s_lshl_b64 s[2:3], s[22:23], 12
	v_lshl_add_u64 v[156:157], s[2:3], 0, v[214:215]
	s_nop 1
	v_mov_b64_e32 v[32:33], s[10:11]
	v_mad_u64_u32 v[32:33], s[2:3], v156, s85, v[32:33]
	v_mad_u32_u24 v33, v157, s85, v33
	s_mul_i32 s80, s47, 12
	s_waitcnt vmcnt(0) lgkmcnt(0)
	s_barrier
	v_lshl_add_u64 v[158:159], v[32:33], 0, s[80:81]
	v_mov_b32_e32 v32, v205
	v_mov_b32_e32 v33, v150
	s_nop 1
	v_permlane32_swap_b32_e32 v150, v33
	v_lshl_add_u32 v34, v191, 2, 0
	s_lshl_b32 s2, s46, 1
	v_add_f32_e32 v33, v150, v33
	v_add_u32_e32 v164, 0x10000, v34
	s_add_u32 s4, s45, s2
	v_div_scale_f32 v34, s[2:3], v33, v33, 1.0
	v_rcp_f32_e32 v35, v34
	v_div_scale_f32 v36, vcc, 1.0, v33, 1.0
	v_cmp_lt_f32_e64 s[2:3], 0, v33
	v_fma_f32 v37, -v34, v35, 1.0
	v_fmac_f32_e32 v35, v37, v35
	v_mul_f32_e32 v37, v36, v35
	v_fma_f32 v38, -v34, v37, v36
	v_fmac_f32_e32 v37, v38, v35
	v_fma_f32 v34, -v34, v37, v36
	v_div_fmas_f32 v34, v34, v35, v37
	v_div_fixup_f32 v33, v34, v33, 1.0
	v_cndmask_b32_e64 v33, 0, v33, s[2:3]
	v_mov_b32_e32 v80, v246
	s_addc_u32 s5, s44, 0
	s_mov_b32 s19, s81
	s_mov_b32 s21, s81
	v_mov_b32_e32 v34, v215
	v_mov_b32_e32 v35, v215
	v_mov_b32_e32 v36, v215
	v_mov_b32_e32 v37, v215
	v_mov_b32_e32 v38, v215
	v_mov_b32_e32 v39, v215
	v_mov_b32_e32 v40, v215
	v_mov_b32_e32 v41, v215
	v_mov_b32_e32 v42, v215
	v_mov_b32_e32 v43, v215
	v_mov_b32_e32 v44, v215
	v_mov_b32_e32 v45, v215
	v_mov_b32_e32 v46, v215
	v_mov_b32_e32 v47, v215
	s_waitcnt vmcnt(0)
	v_mul_f32_e32 v32, v32, v33
	v_mul_f32_e32 v0, v0, v32
	v_mul_f32_e32 v1, v1, v32
	v_mul_f32_e32 v16, v16, v32
	v_mul_f32_e32 v17, v17, v32
	v_mul_f32_e32 v2, v2, v32
	v_mul_f32_e32 v18, v18, v32
	v_mul_f32_e32 v3, v3, v32
	v_mul_f32_e32 v19, v19, v32
	v_mul_f32_e32 v4, v4, v32
	v_mul_f32_e32 v20, v20, v32
	v_mul_f32_e32 v5, v5, v32
	v_mul_f32_e32 v21, v21, v32
	v_mul_f32_e32 v6, v6, v32
	v_mul_f32_e32 v22, v22, v32
	v_mul_f32_e32 v7, v7, v32
	v_mul_f32_e32 v23, v23, v32
	v_mul_f32_e32 v8, v8, v32
	v_mul_f32_e32 v24, v24, v32
	v_mul_f32_e32 v9, v9, v32
	v_mul_f32_e32 v25, v25, v32
	v_mul_f32_e32 v10, v10, v32
	v_mul_f32_e32 v26, v26, v32
	v_mul_f32_e32 v11, v11, v32
	v_mul_f32_e32 v27, v27, v32
	v_mul_f32_e32 v12, v12, v32
	v_mul_f32_e32 v28, v28, v32
	v_mul_f32_e32 v13, v13, v32
	v_mul_f32_e32 v29, v29, v32
	v_mul_f32_e32 v14, v14, v32
	v_mul_f32_e32 v30, v30, v32
	v_mul_f32_e32 v15, v15, v32
	v_mul_f32_e32 v31, v31, v32
	ds_write2st64_b32 v164, v0, v1 offset1:8
	ds_write2st64_b32 v164, v16, v17 offset0:128 offset1:136
	ds_write2st64_b32 v164, v2, v3 offset0:16 offset1:24
	ds_write2st64_b32 v164, v18, v19 offset0:144 offset1:152
	ds_write2st64_b32 v164, v4, v5 offset0:32 offset1:40
	ds_write2st64_b32 v164, v20, v21 offset0:160 offset1:168
	ds_write2st64_b32 v164, v6, v7 offset0:48 offset1:56
	ds_write2st64_b32 v164, v22, v23 offset0:176 offset1:184
	ds_write2st64_b32 v164, v8, v9 offset0:64 offset1:72
	ds_write2st64_b32 v164, v24, v25 offset0:192 offset1:200
	ds_write2st64_b32 v164, v10, v11 offset0:80 offset1:88
	ds_write2st64_b32 v164, v26, v27 offset0:208 offset1:216
	ds_write2st64_b32 v164, v12, v13 offset0:96 offset1:104
	ds_write2st64_b32 v164, v28, v29 offset0:224 offset1:232
	ds_write2st64_b32 v164, v14, v15 offset0:112 offset1:120
	ds_write2st64_b32 v164, v30, v31 offset0:240 offset1:248
	v_mov_b64_e32 v[2:3], s[16:17]
	v_and_b32_e32 v0, 31, v80
	v_bfe_u32 v1, v80, 5, 1
	v_or_b32_e32 v4, s39, v0
	v_mad_u64_u32 v[2:3], s[2:3], v4, s65, v[2:3]
	v_lshlrev_b32_e32 v4, 4, v1
	v_mov_b32_e32 v5, v215
	v_lshl_add_u64 v[2:3], v[2:3], 0, v[4:5]
	global_load_dwordx4 v[112:115], v[2:3], off offset:2368
	global_load_dwordx4 v[116:119], v[2:3], off offset:2400
	global_load_dwordx4 v[120:123], v[2:3], off offset:2432
	global_load_dwordx4 v[124:127], v[2:3], off offset:2464
	v_and_b32_e32 v6, 63, v80
	s_add_i32 s2, s40, 0xfffffe01
	v_mul_u32_u24_e32 v2, 0xa00, v6
	s_lshr_b32 s2, s2, 6
	v_lshlrev_b32_e32 v2, 1, v2
	v_mov_b32_e32 v3, v215
	s_cmpk_gt_u32 s40, 0x1ff
	v_lshl_add_u64 v[2:3], s[4:5], 0, v[2:3]
	s_cselect_b32 s16, s2, 0
	v_lshl_add_u64 v[2:3], v[2:3], 0, s[18:19]
	s_mov_b64 s[2:3], 0x1140
	v_lshl_add_u64 v[160:161], v[2:3], 0, s[2:3]
	v_bfe_u32 v2, v80, 2, 4
	v_or_b32_e32 v2, s59, v2
	v_mul_u32_u24_e32 v2, 0xa00, v2
	v_lshlrev_b32_e32 v2, 1, v2
	v_mov_b32_e32 v3, v215
	v_lshl_add_u64 v[2:3], s[4:5], 0, v[2:3]
	v_lshl_add_u64 v[4:5], v[2:3], 0, s[20:21]
	v_lshlrev_b32_e32 v2, 3, v80
	v_and_b32_e32 v2, 24, v2
	v_lshlrev_b32_e32 v6, 1, v2
	v_mov_b32_e32 v7, v215
	v_lshl_add_u64 v[4:5], v[4:5], 0, v[6:7]
	s_mov_b64 s[2:3], 0x1240
	v_lshl_add_u64 v[162:163], v[4:5], 0, s[2:3]
	s_min_u32 s2, s16, s43
	s_mul_i32 s3, s2, 0x56
	s_lshr_b32 s3, s3, 8
	s_mul_i32 s3, s3, 3
	s_sub_i32 s3, s2, s3
	s_and_b32 s3, s3, 0xff
	s_lshl_b32 s3, s3, 14
	s_add_i32 s3, s3, 0
	s_mul_i32 s80, s2, 0x50000
	v_mov_b32_e32 v32, v215
	v_mov_b32_e32 v33, v215
	v_lshl_add_u64 v[4:5], v[160:161], 0, s[80:81]
	s_add_i32 m0, s3, s89
	s_add_i32 s2, s3, s95
	global_load_lds_dwordx4 v[4:5], off
	s_add_i32 m0, s2, 0x2000
	s_or_b32 s2, s16, 1
	s_min_u32 s2, s2, s43
	s_mul_i32 s3, s2, 0x56
	s_lshr_b32 s3, s3, 8
	s_mul_i32 s3, s3, 3
	s_sub_i32 s3, s2, s3
	v_lshl_add_u64 v[4:5], v[162:163], 0, s[80:81]
	s_and_b32 s3, s3, 0xff
	s_mul_i32 s80, s2, 0x50000
	s_or_b32 s2, s16, 2
	s_lshl_b32 s3, s3, 14
	s_min_u32 s2, s2, s43
	s_add_i32 s4, s3, 0
	s_mul_i32 s3, s2, 0x56
	s_lshr_b32 s3, s3, 8
	s_mul_i32 s3, s3, 3
	s_sub_i32 s3, s2, s3
	s_and_b32 s3, s3, 0xff
	global_load_lds_dwordx4 v[4:5], off
	v_lshl_add_u64 v[4:5], v[160:161], 0, s[80:81]
	s_add_i32 m0, s4, s89
	s_lshl_b32 s5, s3, 14
	s_mul_i32 s2, s2, 0x50000
	s_mov_b32 s3, s81
	global_load_lds_dwordx4 v[4:5], off
	v_lshl_add_u64 v[4:5], v[160:161], 0, s[2:3]
	s_add_i32 m0, s61, s5
	s_add_i32 s2, s4, s95
	global_load_lds_dwordx4 v[4:5], off
	s_add_i32 m0, s2, 0x2000
	s_mul_hi_u32 s2, s16, 0x55555556
	s_mul_i32 s2, s2, 3
	s_sub_i32 s2, s16, s2
	v_lshl_add_u64 v[4:5], v[162:163], 0, s[80:81]
	s_lshl_b32 s2, s2, 14
	global_load_lds_dwordx4 v[4:5], off
	s_add_i32 s2, s2, 0
	v_lshlrev_b32_e32 v166, 10, v1
	v_lshlrev_b32_e32 v167, 4, v0
	s_waitcnt vmcnt(2) lgkmcnt(0)
	s_barrier
; #define AT_KFRAG(t) do { \
;         LAS unsigned char* Kb_ = lds + ((t) % 3) * SLOT + hi * 1024 + r32 * 16; \
;         _Pragma("unroll") for (int ds = 0; ds < NDS; ++ds) { kf[2 * ds] = *(LAS bf16x8*)(Kb_ + ds * 2048); kf[2 * ds + 1] = *(LAS bf16x8*)(Kb_ + ds * 2048 + 512); } } while (0)
; template <int DQK, int MODE> ...
;     ...
;     o[0] = f32x16{}; o[1] = f32x16{};
;     float m_run = 0.f, l_run = 0.f; bool init = false;
;     f32x16 negm = f32x16{}; asm volatile("" : "+v"(negm));
;     f32x16 pa0 = f32x16{}, pa1 = f32x16{}, pb0 = f32x16{}, pb1 = f32x16{};
;     ...
;     { AT_KFRAG(kt_lo); asm volatile("s_waitcnt lgkmcnt(0)\n\ts_barrier" ::: "memory");
;       const float b_ = AT_BIAS(kt_lo); AT_QKM(pa0, pa1, AT_SPLAT(b_)); }
;     const int vfo = ((lane >> 4) & 1) * 32 + (lane & 3) * 8 + (4 * hi + ((lane & 15) >> 2)) * 64;
	v_add3_u32 v3, s2, v166, v167
	ds_read_b128 v[4:7], v3
	s_waitcnt vmcnt(2) lgkmcnt(0)
	v_mfma_f32_32x32x16_bf16 v[48:63], v[4:7], v[112:115], 0
	ds_read_b128 v[4:7], v3 offset:512
	s_cmp_gt_u32 s16, s43
	s_waitcnt lgkmcnt(0)
	v_mfma_f32_32x32x16_bf16 v[64:79], v[4:7], v[112:115], 0
	ds_read_b128 v[4:7], v3 offset:2048
	s_waitcnt lgkmcnt(0)
	v_mfma_f32_32x32x16_bf16 v[48:63], v[4:7], v[116:119], v[48:63]
	ds_read_b128 v[4:7], v3 offset:2560
	s_waitcnt lgkmcnt(0)
	v_mfma_f32_32x32x16_bf16 v[64:79], v[4:7], v[116:119], v[64:79]
	ds_read_b128 v[4:7], v3 offset:4096
	s_waitcnt lgkmcnt(0)
	v_mfma_f32_32x32x16_bf16 v[48:63], v[4:7], v[120:123], v[48:63]
	ds_read_b128 v[4:7], v3 offset:4608
	s_waitcnt lgkmcnt(0)
	v_mfma_f32_32x32x16_bf16 v[64:79], v[4:7], v[120:123], v[64:79]
	ds_read_b128 v[4:7], v3 offset:6144
	s_waitcnt lgkmcnt(0)
	v_mfma_f32_32x32x16_bf16 v[48:63], v[4:7], v[124:127], v[48:63]
	ds_read_b128 v[4:7], v3 offset:6656
	s_waitcnt lgkmcnt(0)
	s_barrier
	s_waitcnt lgkmcnt(0)
	v_mfma_f32_32x32x16_bf16 v[64:79], v[4:7], v[124:127], v[64:79]
	s_cbranch_scc1 .LBB0_711
	v_lshlrev_b32_e32 v5, 4, v80
	v_lshlrev_b32_e32 v4, 2, v1
	s_lshl_b32 s2, s16, 14
	v_lshlrev_b32_e32 v1, 8, v1
	v_and_b32_e32 v5, 0xc0, v5
	v_lshlrev_b32_e32 v3, 1, v80
	v_or3_b32 v1, s2, v1, v5
	s_add_i32 s2, s56, s40
	v_and_b32_e32 v3, 32, v3
	v_add_u32_e32 v0, s2, v0
	v_or3_b32 v1, v1, v3, v2
	v_sub_u32_e32 v0, v0, v4
	s_lshl_b32 s20, s16, 6
	v_mov_b32_e32 v171, 0
	v_add3_u32 v168, 0, v166, v167
	s_add_i32 s17, s39, 0xfffffe20
	s_add_i32 s18, s16, 4
	v_add_u32_e32 v169, 0, v1
	s_add_i32 s19, s16, 1
	v_subrev_u32_e32 v170, s20, v0
	s_mov_b64 s[2:3], 0
	v_mov_b32_e32 v165, 0
	v_mov_b32_e32 v16, 0
	v_mov_b32_e32 v17, v171
	v_mov_b32_e32 v18, v171
	v_mov_b32_e32 v19, v171
	v_mov_b32_e32 v20, v171
	v_mov_b32_e32 v21, v171
	v_mov_b32_e32 v22, v171
	v_mov_b32_e32 v23, v171
	v_mov_b32_e32 v24, v171
	v_mov_b32_e32 v25, v171
	v_mov_b32_e32 v26, v171
	v_mov_b32_e32 v27, v171
	v_mov_b32_e32 v28, v171
	v_mov_b32_e32 v29, v171
	v_mov_b32_e32 v30, v171
	v_mov_b32_e32 v31, v171
	v_mov_b32_e32 v0, v171
	v_mov_b32_e32 v1, v171
	v_mov_b32_e32 v2, v171
	v_mov_b32_e32 v3, v171
	v_mov_b32_e32 v4, v171
	v_mov_b32_e32 v5, v171
	v_mov_b32_e32 v6, v171
	v_mov_b32_e32 v7, v171
	v_mov_b32_e32 v8, v171
	v_mov_b32_e32 v9, v171
	v_mov_b32_e32 v10, v171
	v_mov_b32_e32 v11, v171
	v_mov_b32_e32 v12, v171
	v_mov_b32_e32 v13, v171
	v_mov_b32_e32 v14, v171
	v_mov_b32_e32 v15, v171
	v_readfirstlane_b32 s86, v160
	v_readfirstlane_b32 s87, v161
	v_readfirstlane_b32 s98, v162
	v_readfirstlane_b32 s99, v163
	s_nop 1
	v_subrev_u32_e32 v200, s86, v160
	v_subrev_u32_e32 v202, s98, v162
	s_branch .LBB0_702

; __device__ __forceinline__ float oload(LAS unsigned char* lds, int tid, int i) { return ((LAS float*)(lds + OSAVE_OFF) + tid)[i * 512]; }
; __device__ __forceinline__ void attn_phase(LAS unsigned char* lds, int* counter, const bf16_t* __restrict__ P, const bf16_t* __restrict__ Qm, const bf16_t* __restrict__ Kmla, ...
;     ...
;             const float g0 = gates[row * 24 + head * 3 + 0], sc2 = linv * gates[row * 24 + head * 3 + 2];
;             const bf16_t* oc = ocmp + row * 512 + head * 64;
; #pragma unroll
;             for (int dh = 0; dh < 2; ++dh)
; #pragma unroll
;                 for (int a = 0; a < 4; ++a) {
;                     const u32x2 raw = *(const u32x2*)(oc + 32 * dh + 8 * a + 4 * hi);
;                     const float c0 = __uint_as_float(raw.x << 16), c1 = __uint_as_float(raw.x & 0xffff0000u), c2 = __uint_as_float(raw.y << 16), c3 = __uint_as_float(raw.y & 0xffff0000u);
;                     o[dh][4 * a + 0] = o[dh][4 * a + 0] * sc2 + oload(lds, tid, 16 * dh + 4 * a + 0) + g0 * c0;
;                     o[dh][4 * a + 1] = o[dh][4 * a + 1] * sc2 + oload(lds, tid, 16 * dh + 4 * a + 1) + g0 * c1;
;                     o[dh][4 * a + 2] = o[dh][4 * a + 2] * sc2 + oload(lds, tid, 16 * dh + 4 * a + 2) + g0 * c2;
;                     o[dh][4 * a + 3] = o[dh][4 * a + 3] * sc2 + oload(lds, tid, 16 * dh + 4 * a + 3) + g0 * c3;
;                 }
.LBB0_712:
	v_readlane_b32 s86, v254, 37
	v_readlane_b32 s87, v254, 38
	s_waitcnt vmcnt(0) lgkmcnt(0)
	s_barrier
	s_nop 3
	v_mov_b32_e32 v70, v206
	v_lshlrev_b64 v[32:33], 10, v[156:157]
	s_lshl_b32 s80, s42, 1
	v_lshl_add_u64 v[32:33], s[8:9], 0, v[32:33]
	v_lshlrev_b32_e32 v34, 3, v190
	v_mov_b32_e32 v35, v215
	v_lshl_add_u64 v[32:33], v[32:33], 0, s[80:81]
	v_lshl_add_u64 v[34:35], v[32:33], 0, v[34:35]
	v_mov_b32_e32 v36, v208
	v_mov_b32_e32 v37, v209
	v_mov_b32_e32 v38, v210
	v_mov_b32_e32 v39, v211
	v_mov_b32_e32 v40, v212
	v_mov_b32_e32 v41, v213
	v_mov_b32_e32 v42, v216
	v_mov_b32_e32 v43, v217
	v_mov_b32_e32 v44, v218
	v_mov_b32_e32 v45, v219
	v_mov_b32_e32 v32, v204
	v_mov_b32_e32 v46, v220
	v_mov_b32_e32 v47, v221
	v_mov_b32_e32 v48, v230
	v_mov_b32_e32 v49, v231
	ds_read2st64_b32 v[50:51], v164 offset1:8
	ds_read2st64_b32 v[52:53], v164 offset0:16 offset1:24
	ds_read2st64_b32 v[54:55], v164 offset0:32 offset1:40
	ds_read2st64_b32 v[56:57], v164 offset0:48 offset1:56
	v_mov_b32_e32 v34, v232
	v_mov_b32_e32 v35, v233
	v_mov_b32_e32 v33, v165
	s_nop 1
	v_permlane32_swap_b32_e32 v165, v33
	v_add_f32_e32 v33, v165, v33
	v_div_scale_f32 v71, s[2:3], v33, v33, 1.0
	v_rcp_f32_e32 v72, v71
	v_div_scale_f32 v73, vcc, 1.0, v33, 1.0
	ds_read2st64_b32 v[58:59], v164 offset0:64 offset1:72
	ds_read2st64_b32 v[60:61], v164 offset0:80 offset1:88
	ds_read2st64_b32 v[62:63], v164 offset0:96 offset1:104
	ds_read2st64_b32 v[64:65], v164 offset0:112 offset1:120
	ds_read2st64_b32 v[66:67], v164 offset0:128 offset1:136
	v_fma_f32 v74, -v71, v72, 1.0
	v_fmac_f32_e32 v72, v74, v72
	v_mul_f32_e32 v74, v73, v72
	v_fma_f32 v75, -v71, v74, v73
	v_fmac_f32_e32 v74, v75, v72
	v_fma_f32 v71, -v71, v74, v73
	ds_read2st64_b32 v[68:69], v164 offset0:144 offset1:152
	v_div_fmas_f32 v71, v71, v72, v74
	v_div_fixup_f32 v71, v71, v33, 1.0
	v_cmp_lt_f32_e32 vcc, 0, v33
	v_readlane_b32 s2, v254, 46
	v_readlane_b32 s3, v254, 47
	v_cndmask_b32_e32 v33, 0, v71, vcc
	v_cmp_eq_u32_e32 vcc, 0, v190
	s_waitcnt vmcnt(0)
	v_mul_f32_e32 v70, v70, v33
	s_waitcnt lgkmcnt(9)
	v_pk_fma_f32 v[16:17], v[16:17], v[70:71], v[50:51] op_sel_hi:[1,0,1]
	s_waitcnt lgkmcnt(8)
	v_pk_fma_f32 v[18:19], v[18:19], v[70:71], v[52:53] op_sel_hi:[1,0,1]
	s_waitcnt lgkmcnt(1)
	v_pk_fma_f32 v[50:51], v[0:1], v[70:71], v[66:67] op_sel_hi:[1,0,1]
	v_lshlrev_b32_e32 v0, 16, v36
	v_and_b32_e32 v1, 0xffff0000, v36
	v_lshlrev_b32_e32 v36, 16, v37
	v_and_b32_e32 v37, 0xffff0000, v37
	v_pk_fma_f32 v[0:1], v[32:33], v[0:1], v[16:17] op_sel_hi:[0,1,1]
	v_pk_fma_f32 v[16:17], v[32:33], v[36:37], v[18:19] op_sel_hi:[0,1,1]
	s_waitcnt lgkmcnt(0)
	v_pk_fma_f32 v[36:37], v[2:3], v[70:71], v[68:69] op_sel_hi:[1,0,1]
	ds_read2st64_b32 v[2:3], v164 offset0:176 offset1:184
	v_pk_fma_f32 v[20:21], v[20:21], v[70:71], v[54:55] op_sel_hi:[1,0,1]
	v_pk_fma_f32 v[22:23], v[22:23], v[70:71], v[56:57] op_sel_hi:[1,0,1]
	v_pk_fma_f32 v[24:25], v[24:25], v[70:71], v[58:59] op_sel_hi:[1,0,1]
	v_pk_fma_f32 v[26:27], v[26:27], v[70:71], v[60:61] op_sel_hi:[1,0,1]
	s_waitcnt lgkmcnt(0)
	v_pk_fma_f32 v[6:7], v[6:7], v[70:71], v[2:3] op_sel_hi:[1,0,1]
	ds_read2st64_b32 v[2:3], v164 offset0:208 offset1:216
	v_pk_fma_f32 v[28:29], v[28:29], v[70:71], v[62:63] op_sel_hi:[1,0,1]
	v_pk_fma_f32 v[30:31], v[30:31], v[70:71], v[64:65] op_sel_hi:[1,0,1]
	v_lshlrev_b32_e32 v52, 16, v38
	v_and_b32_e32 v53, 0xffff0000, v38
	v_lshlrev_b32_e32 v38, 16, v39
	v_and_b32_e32 v39, 0xffff0000, v39
	v_lshlrev_b32_e32 v54, 16, v40
	v_and_b32_e32 v55, 0xffff0000, v40
	v_lshlrev_b32_e32 v40, 16, v41
	v_and_b32_e32 v41, 0xffff0000, v41
	v_lshlrev_b32_e32 v56, 16, v42
	v_and_b32_e32 v57, 0xffff0000, v42
	v_lshlrev_b32_e32 v42, 16, v43
	v_and_b32_e32 v43, 0xffff0000, v43
	v_pk_fma_f32 v[18:19], v[32:33], v[52:53], v[20:21] op_sel_hi:[0,1,1]
	v_pk_fma_f32 v[20:21], v[32:33], v[38:39], v[22:23] op_sel_hi:[0,1,1]
	v_pk_fma_f32 v[22:23], v[32:33], v[54:55], v[24:25] op_sel_hi:[0,1,1]
	v_pk_fma_f32 v[24:25], v[32:33], v[40:41], v[26:27] op_sel_hi:[0,1,1]
	v_pk_fma_f32 v[26:27], v[32:33], v[56:57], v[28:29] op_sel_hi:[0,1,1]
	v_pk_fma_f32 v[28:29], v[32:33], v[42:43], v[30:31] op_sel_hi:[0,1,1]
	ds_read2st64_b32 v[30:31], v164 offset0:160 offset1:168
	s_waitcnt lgkmcnt(1)
; __device__ __forceinline__ unsigned cvtpk(float lo, float hi) { f32x2 v = {lo, hi}; bf16x2_t b = __builtin_convertvector(v, bf16x2_t); return __builtin_bit_cast(unsigned, b); }
; __device__ __forceinline__ float oload(LAS unsigned char* lds, int tid, int i) { return ((LAS float*)(lds + OSAVE_OFF) + tid)[i * 512]; }
; __device__ __forceinline__ void store_o_bf16(bf16_t* dst, const f32x16 (&o)[2], int hi) {
; #pragma unroll
;     for (int dh = 0; dh < 2; ++dh)
; #pragma unroll
;         for (int ap = 0; ap < 2; ++ap) {
;             const int a0 = 2 * ap, a1 = a0 + 1;
;             unsigned x0 = cvtpk(o[dh][4 * a0], o[dh][4 * a0 + 1]), x1 = cvtpk(o[dh][4 * a0 + 2], o[dh][4 * a0 + 3]);
;             unsigned y0 = cvtpk(o[dh][4 * a1], o[dh][4 * a1 + 1]), y1 = cvtpk(o[dh][4 * a1 + 2], o[dh][4 * a1 + 3]);
;             const auto r0 = __builtin_amdgcn_permlane32_swap(x0, y0, false, false);
;             const auto r1 = __builtin_amdgcn_permlane32_swap(x1, y1, false, false);
;             const u32x4 w = {r0[0], r1[0], r0[1], r1[1]};
;             *(u32x4*)(dst + 32 * dh + 8 * (hi ? a1 : a0)) = w;
;         }
; }
; __device__ __forceinline__ void attn_phase(LAS unsigned char* lds, int* counter, const bf16_t* __restrict__ P, const bf16_t* __restrict__ Qm, const bf16_t* __restrict__ Kmla, ...
;     ...
;                     o[dh][4 * a + 0] = o[dh][4 * a + 0] * sc2 + oload(lds, tid, 16 * dh + 4 * a + 0) + g0 * c0;
;                     o[dh][4 * a + 1] = o[dh][4 * a + 1] * sc2 + oload(lds, tid, 16 * dh + 4 * a + 1) + g0 * c1;
;                     o[dh][4 * a + 2] = o[dh][4 * a + 2] * sc2 + oload(lds, tid, 16 * dh + 4 * a + 2) + g0 * c2;
;                     o[dh][4 * a + 3] = o[dh][4 * a + 3] * sc2 + oload(lds, tid, 16 * dh + 4 * a + 3) + g0 * c3;
;                 }
;             store_o_bf16(Omix + row * DM + 512 + head * 64, o, hi);
	v_pk_fma_f32 v[10:11], v[10:11], v[70:71], v[2:3] op_sel_hi:[1,0,1]
	ds_read2st64_b32 v[2:3], v164 offset0:240 offset1:248
	v_lshlrev_b32_e32 v38, 16, v46
	v_and_b32_e32 v39, 0xffff0000, v46
	s_waitcnt lgkmcnt(1)
	v_pk_fma_f32 v[4:5], v[4:5], v[70:71], v[30:31] op_sel_hi:[1,0,1]
	v_lshlrev_b32_e32 v30, 16, v47
	v_and_b32_e32 v31, 0xffff0000, v47
	ds_read2st64_b32 v[46:47], v164 offset0:224 offset1:232
	s_waitcnt lgkmcnt(1)
	v_pk_fma_f32 v[14:15], v[14:15], v[70:71], v[2:3] op_sel_hi:[1,0,1]
	v_lshlrev_b64 v[2:3], 11, v[156:157]
	v_lshl_add_u64 v[2:3], s[2:3], 0, v[2:3]
	ds_read2st64_b32 v[40:41], v164 offset0:192 offset1:200
	s_waitcnt lgkmcnt(1)
	v_pk_fma_f32 v[12:13], v[12:13], v[70:71], v[46:47] op_sel_hi:[1,0,1]
	v_lshl_add_u64 v[46:47], v[2:3], 0, s[80:81]
	v_cvt_pk_bf16_f32 v0, v0, v1
	v_cvt_pk_bf16_f32 v1, v16, v17
	v_cvt_pk_bf16_f32 v2, v18, v19
	v_cvt_pk_bf16_f32 v3, v20, v21
	v_lshlrev_b32_e32 v16, 4, v190
	v_mov_b32_e32 v17, v215
	v_permlane32_swap_b32_e32 v0, v2
	v_permlane32_swap_b32_e32 v1, v3
	v_lshl_add_u64 v[16:17], v[46:47], 0, v[16:17]
	global_store_dwordx4 v[16:17], v[0:3], off offset:1024
	v_cndmask_b32_e64 v18, 48, 32, vcc
	v_mov_b32_e32 v19, v215
	v_cvt_pk_bf16_f32 v0, v22, v23
	v_cvt_pk_bf16_f32 v1, v24, v25
	v_cvt_pk_bf16_f32 v2, v26, v27
	v_cvt_pk_bf16_f32 v3, v28, v29
	v_lshlrev_b32_e32 v58, 16, v44
	v_and_b32_e32 v59, 0xffff0000, v44
	v_lshlrev_b32_e32 v44, 16, v45
	v_and_b32_e32 v45, 0xffff0000, v45
	v_permlane32_swap_b32_e32 v0, v2
	v_permlane32_swap_b32_e32 v1, v3
	v_lshl_add_u64 v[18:19], v[46:47], 0, v[18:19]
	global_store_dwordx4 v[18:19], v[0:3], off offset:1024
	v_pk_fma_f32 v[4:5], v[32:33], v[38:39], v[4:5] op_sel_hi:[0,1,1]
	v_pk_fma_f32 v[6:7], v[32:33], v[30:31], v[6:7] op_sel_hi:[0,1,1]
	v_pk_fma_f32 v[0:1], v[32:33], v[58:59], v[50:51] op_sel_hi:[0,1,1]
	v_pk_fma_f32 v[2:3], v[32:33], v[44:45], v[36:37] op_sel_hi:[0,1,1]
	v_lshlrev_b32_e32 v42, 16, v48
	v_and_b32_e32 v43, 0xffff0000, v48
	s_waitcnt lgkmcnt(0)
	v_pk_fma_f32 v[8:9], v[8:9], v[70:71], v[40:41] op_sel_hi:[1,0,1]
	v_lshlrev_b32_e32 v40, 16, v49
	v_and_b32_e32 v41, 0xffff0000, v49
	v_lshlrev_b32_e32 v48, 16, v34
	v_and_b32_e32 v49, 0xffff0000, v34
	v_lshlrev_b32_e32 v34, 16, v35
	v_and_b32_e32 v35, 0xffff0000, v35
	v_cvt_pk_bf16_f32 v0, v0, v1
	v_cvt_pk_bf16_f32 v1, v2, v3
	v_cvt_pk_bf16_f32 v2, v4, v5
	v_cvt_pk_bf16_f32 v3, v6, v7
	v_pk_fma_f32 v[8:9], v[32:33], v[42:43], v[8:9] op_sel_hi:[0,1,1]
	v_pk_fma_f32 v[10:11], v[32:33], v[40:41], v[10:11] op_sel_hi:[0,1,1]
	v_pk_fma_f32 v[12:13], v[32:33], v[48:49], v[12:13] op_sel_hi:[0,1,1]
	v_pk_fma_f32 v[14:15], v[32:33], v[34:35], v[14:15] op_sel_hi:[0,1,1]
	v_permlane32_swap_b32_e32 v0, v2
	v_permlane32_swap_b32_e32 v1, v3
	global_store_dwordx4 v[16:17], v[0:3], off offset:1088
	s_mov_b64 s[2:3], 0
	s_nop 0
	v_cvt_pk_bf16_f32 v0, v8, v9
	v_cvt_pk_bf16_f32 v1, v10, v11
	v_cvt_pk_bf16_f32 v2, v12, v13
	v_cvt_pk_bf16_f32 v3, v14, v15
	s_nop 0
	v_permlane32_swap_b32_e32 v0, v2
	v_permlane32_swap_b32_e32 v1, v3
	global_store_dwordx4 v[18:19], v[0:3], off offset:1088
